# final RMSNorm phase: g_final loads hoisted out of the row loop into registers; per-chunk load/wait/store chain removed
# speedup vs baseline: 1.0069x; 1.0069x over previous
;     __device__ __forceinline__ bf16_t* bfp(size_t off) const { return (bf16_t*)(ws + off); }
; __device__ void phase_final(const Ctx& c) {
;     const bf16_t* xw = c.bfp(WS_XW); const float* g = c.p->in[22]; float* out = c.p->out;
;     for (int row = c.bid * 8 + c.wave; row < TL; row += c.G * 8) {
;         f32x4 v[8]; load_row32(v, xw, false, (size_t)row * DM, c.lane);
;         float ss = 0.f;
; #pragma unroll
;         for (int i = 0; i < 8; ++i) ss += v[i][0] * v[i][0] + v[i][1] * v[i][1] + v[i][2] * v[i][2] + v[i][3] * v[i][3];
;         ss = wave_sum(ss, c.lane);
;         const float rstd = rsqrtf(ss * (1.f / DM) + EPS);
; #pragma unroll
;         for (int i = 0; i < 8; ++i) { const int cc = (i >> 1) * 512 + c.lane * 8 + 4 * (i & 1); const f32x4 gg = *(const f32x4*)(g + cc); f32x4 y;
.LBB0_2008:
	s_mov_b32 s2, 0
	s_waitcnt lgkmcnt(0)
	s_barrier
	s_movk_i32 s3, 0x2000
	v_mbcnt_lo_u32_b32 v0, -1, s2
	v_mbcnt_hi_u32_b32 v0, -1, v0
	v_lshl_or_b32 v1, s33, 6, v0
	v_readfirstlane_b32 s2, v217
	s_lshl_b32 s2, s2, 3
	v_ashrrev_i32_e32 v0, 6, v1
	v_add_u32_e32 v18, s2, v0
	v_cmp_gt_i32_e32 vcc, s3, v18
	s_and_saveexec_b64 s[4:5], vcc
	s_cbranch_execz .LBB0_2011
	v_and_b32_e32 v16, 63, v1
	s_load_dwordx4 s[4:7], s[0:1], 0xb0
	s_load_dwordx2 s[8:9], s[0:1], 0xc0
	v_lshlrev_b32_e32 v1, 2, v16
	v_xor_b32_e32 v19, 0x80, v1
	v_xor_b32_e32 v20, 64, v1
	v_xor_b32_e32 v21, 32, v1
	v_xor_b32_e32 v22, 16, v1
	v_xor_b32_e32 v23, 8, v1
	v_xor_b32_e32 v24, 4, v1
	v_ashrrev_i32_e32 v1, 31, v0
	s_ashr_i32 s3, s2, 31
	v_lshl_add_u64 v[0:1], v[0:1], 0, s[2:3]
	v_lshlrev_b32_e32 v2, 5, v16
	v_mov_b32_e32 v3, 0
	v_lshlrev_b64 v[14:15], 13, v[0:1]
	v_lshlrev_b64 v[0:1], 12, v[0:1]
	v_or_b32_e32 v6, 0x1000, v2
	v_mov_b32_e32 v7, v3
	v_or_b32_e32 v8, 0x1010, v2
	v_mov_b32_e32 v9, v3
	v_or_b32_e32 v10, 0x1800, v2
	v_mov_b32_e32 v11, v3
	v_or_b32_e32 v12, 0x1810, v2
	v_mov_b32_e32 v13, v3
	s_lshl_b32 s0, s38, 3
	v_or_b32_e32 v14, v14, v2
	v_lshl_or_b32 v0, v16, 4, v0
	s_waitcnt lgkmcnt(0)
	v_lshl_add_u64 v[4:5], s[4:5], 0, v[2:3]
	v_lshl_add_u64 v[6:7], s[4:5], 0, v[6:7]
	v_lshl_add_u64 v[8:9], s[4:5], 0, v[8:9]
	v_lshl_add_u64 v[10:11], s[4:5], 0, v[10:11]
	v_lshl_add_u64 v[12:13], s[4:5], 0, v[12:13]
	v_lshl_add_u64 v[2:3], s[6:7], 0, v[14:15]
	s_mov_b64 s[2:3], 0x1810
	s_ashr_i32 s1, s0, 31
	v_lshl_add_u64 v[0:1], s[8:9], 0, v[0:1]
	s_mov_b64 s[4:5], 0x12178800
	v_lshl_add_u64 v[14:15], v[2:3], 0, s[2:3]
	s_lshl_b64 s[2:3], s[0:1], 13
	v_lshl_add_u64 v[16:17], v[0:1], 0, s[4:5]
	s_lshl_b64 s[4:5], s[0:1], 12
	s_mov_b64 s[6:7], 0
	v_mov_b32_e32 v25, 0x358637bd
	s_mov_b32 s1, 0x800000
	s_movk_i32 s8, 0xf000
	s_movk_i32 s9, 0x1fff
	global_load_dwordx4 v[100:103], v[4:5], off
	global_load_dwordx4 v[104:107], v[4:5], off offset:16
	global_load_dwordx4 v[108:111], v[4:5], off offset:2048
	global_load_dwordx4 v[112:115], v[4:5], off offset:2064
	global_load_dwordx4 v[116:119], v[6:7], off
	global_load_dwordx4 v[120:123], v[8:9], off
	global_load_dwordx4 v[124:127], v[10:11], off
	global_load_dwordx4 v[128:131], v[12:13], off
	s_waitcnt vmcnt(0)
; __device__ void phase_final(const Ctx& c) {
;     ...
;     for (int row = c.bid * 8 + c.wave; row < TL; row += c.G * 8) {
;         f32x4 v[8]; load_row32(v, xw, false, (size_t)row * DM, c.lane);
;         float ss = 0.f;
; #pragma unroll
;         for (int i = 0; i < 8; ++i) ss += v[i][0] * v[i][0] + v[i][1] * v[i][1] + v[i][2] * v[i][2] + v[i][3] * v[i][3];
;         ss = wave_sum(ss, c.lane);
;         const float rstd = rsqrtf(ss * (1.f / DM) + EPS);
; #pragma unroll
;         for (int i = 0; i < 8; ++i) { const int cc = (i >> 1) * 512 + c.lane * 8 + 4 * (i & 1); const f32x4 gg = *(const f32x4*)(g + cc); f32x4 y;
; #pragma unroll
;             for (int j = 0; j < 4; ++j) y[j] = v[i][j] * rstd * gg[j];
;             *(f32x4*)(out + (size_t)row * DM + cc) = y; }
;     }
.LBB0_2010:
	global_load_dwordx4 v[26:29], v[16:17], off offset:-2048
	global_load_dwordx4 v[30:33], v[16:17], off offset:-1024
	global_load_dwordx4 v[34:37], v[16:17], off
	global_load_dwordx4 v[38:41], v[16:17], off offset:1024
	v_mov_b64_e32 v[0:1], v[100:101]
	v_mov_b64_e32 v[2:3], v[102:103]
	v_add_co_u32_e32 v42, vcc, s8, v14
	v_add_u32_e32 v18, s0, v18
	s_nop 0
	v_addc_co_u32_e32 v43, vcc, -1, v15, vcc
	v_lshl_add_u64 v[16:17], v[16:17], 0, s[4:5]
	s_waitcnt vmcnt(0)
	v_lshlrev_b32_e32 v44, 16, v26
	v_and_b32_e32 v45, 0xffff0000, v26
	v_lshlrev_b32_e32 v46, 16, v28
	v_and_b32_e32 v47, 0xffff0000, v28
	v_and_b32_e32 v57, 0xffff0000, v38
	v_and_b32_e32 v59, 0xffff0000, v40
	v_lshlrev_b32_e32 v26, 16, v27
	v_and_b32_e32 v27, 0xffff0000, v27
	v_lshlrev_b32_e32 v28, 16, v29
	v_and_b32_e32 v29, 0xffff0000, v29
	v_lshlrev_b32_e32 v48, 16, v30
	v_and_b32_e32 v49, 0xffff0000, v30
	v_lshlrev_b32_e32 v56, 16, v38
	v_lshlrev_b32_e32 v58, 16, v40
	v_pk_mul_f32 v[60:61], v[44:45], v[44:45]
	v_pk_mul_f32 v[64:65], v[46:47], v[46:47]
	v_mov_b32_e32 v86, v59
	v_mov_b32_e32 v87, v57
	v_lshlrev_b32_e32 v30, 16, v31
	v_and_b32_e32 v31, 0xffff0000, v31
	v_lshlrev_b32_e32 v50, 16, v32
	v_and_b32_e32 v51, 0xffff0000, v32
	v_and_b32_e32 v53, 0xffff0000, v34
	v_and_b32_e32 v55, 0xffff0000, v36
	v_lshlrev_b32_e32 v38, 16, v39
	v_lshlrev_b32_e32 v40, 16, v41
	v_pk_mul_f32 v[62:63], v[26:27], v[26:27]
	v_pk_mul_f32 v[66:67], v[28:29], v[28:29]
	v_pk_mul_f32 v[68:69], v[48:49], v[48:49]
	v_mov_b32_e32 v84, v58
	v_mov_b32_e32 v85, v56
	v_pk_mul_f32 v[86:87], v[86:87], v[86:87]
	v_add_f32_e32 v92, v64, v65
	v_add_f32_e32 v93, v60, v61
	v_lshlrev_b32_e32 v32, 16, v33
	v_and_b32_e32 v33, 0xffff0000, v33
	v_lshlrev_b32_e32 v52, 16, v34
	v_lshlrev_b32_e32 v54, 16, v36
	v_and_b32_e32 v39, 0xffff0000, v39
	v_and_b32_e32 v41, 0xffff0000, v41
	v_pk_mul_f32 v[70:71], v[30:31], v[30:31]
	v_pk_mul_f32 v[72:73], v[50:51], v[50:51]
	v_mov_b32_e32 v78, v55
	v_mov_b32_e32 v79, v53
	v_mov_b32_e32 v88, v40
	v_mov_b32_e32 v89, v38
	v_add_f32_e32 v68, v68, v69
	v_pk_fma_f32 v[64:65], v[84:85], v[84:85], v[86:87]
	v_add_f32_e32 v66, v66, v92
	v_add_f32_e32 v62, v62, v93
	v_lshlrev_b32_e32 v34, 16, v35
	v_lshlrev_b32_e32 v36, 16, v37
	v_pk_mul_f32 v[74:75], v[32:33], v[32:33]
	v_mov_b32_e32 v76, v54
	v_mov_b32_e32 v77, v52
	v_mov_b32_e32 v90, v41
	v_mov_b32_e32 v91, v39
	v_pk_mul_f32 v[78:79], v[78:79], v[78:79]
	v_add_f32_e32 v69, v72, v73
	v_add_f32_e32 v68, v70, v68
	v_pk_fma_f32 v[64:65], v[88:89], v[88:89], v[64:65]
	v_add_f32_e32 v66, v67, v66
	v_add_f32_e32 v67, v63, v62
	v_and_b32_e32 v35, 0xffff0000, v35
	v_and_b32_e32 v37, 0xffff0000, v37
	v_mov_b32_e32 v80, v36
	v_mov_b32_e32 v81, v34
	v_pk_fma_f32 v[60:61], v[76:77], v[76:77], v[78:79]
	v_add_f32_e32 v69, v74, v69
	v_add_f32_e32 v68, v71, v68
	v_pk_fma_f32 v[62:63], v[90:91], v[90:91], v[64:65]
	v_add_f32_e32 v64, v67, v66
	v_mov_b32_e32 v82, v37
	v_mov_b32_e32 v83, v35
	v_pk_fma_f32 v[60:61], v[80:81], v[80:81], v[60:61]
	v_add_f32_e32 v69, v75, v69
	v_add_f32_e32 v64, v64, v68
	v_pk_fma_f32 v[60:61], v[82:83], v[82:83], v[60:61]
	v_add_f32_e32 v64, v69, v64
	v_add_f32_e32 v61, v61, v64
	v_add_f32_e32 v60, v60, v61
	v_add_f32_e32 v60, v63, v60
	v_add_f32_e32 v60, v62, v60
	ds_bpermute_b32 v61, v19, v60
	s_waitcnt lgkmcnt(0)
	v_add_f32_e32 v60, v60, v61
	ds_bpermute_b32 v61, v20, v60
	s_waitcnt lgkmcnt(0)
	v_add_f32_e32 v60, v60, v61
	ds_bpermute_b32 v61, v21, v60
	s_waitcnt lgkmcnt(0)
	v_add_f32_e32 v60, v60, v61
	ds_bpermute_b32 v61, v22, v60
	s_waitcnt lgkmcnt(0)
	v_add_f32_e32 v60, v60, v61
	ds_bpermute_b32 v61, v23, v60
	s_waitcnt lgkmcnt(0)
	v_add_f32_e32 v60, v60, v61
	ds_bpermute_b32 v61, v24, v60
	s_waitcnt lgkmcnt(0)
	v_add_f32_e32 v60, v60, v61
	v_fmamk_f32 v60, v60, 0x3a000000, v25
	v_mul_f32_e32 v61, 0x4b800000, v60
	v_cmp_gt_f32_e32 vcc, s1, v60
	s_nop 1
	v_cndmask_b32_e32 v60, v60, v61, vcc
	v_rsq_f32_e32 v60, v60
	s_nop 0
	v_mul_f32_e32 v61, 0x45800000, v60
	v_cndmask_b32_e32 v60, v60, v61, vcc
	v_pk_mul_f32 v[44:45], v[60:61], v[44:45] op_sel_hi:[0,1]
	v_pk_mul_f32 v[26:27], v[60:61], v[26:27] op_sel_hi:[0,1]
	v_pk_mul_f32 v[2:3], v[2:3], v[26:27]
	v_pk_mul_f32 v[0:1], v[0:1], v[44:45]
	global_store_dwordx4 v[42:43], v[0:3], off offset:-2064
	v_pk_mul_f32 v[26:27], v[60:61], v[28:29] op_sel_hi:[0,1]
	v_pk_mul_f32 v[28:29], v[60:61], v[46:47] op_sel_hi:[0,1]
	v_cmp_lt_i32_e32 vcc, s9, v18
	s_or_b64 s[6:7], vcc, s[6:7]
	v_mov_b64_e32 v[0:1], v[104:105]
	v_mov_b64_e32 v[2:3], v[106:107]
	v_pk_mul_f32 v[0:1], v[0:1], v[28:29]
	v_pk_mul_f32 v[2:3], v[2:3], v[26:27]
	global_store_dwordx4 v[42:43], v[0:3], off offset:-2048
	v_pk_mul_f32 v[26:27], v[60:61], v[30:31] op_sel_hi:[0,1]
	v_pk_mul_f32 v[28:29], v[60:61], v[48:49] op_sel_hi:[0,1]
	v_mov_b64_e32 v[0:1], v[108:109]
	v_mov_b64_e32 v[2:3], v[110:111]
	v_pk_mul_f32 v[0:1], v[0:1], v[28:29]
	v_pk_mul_f32 v[2:3], v[2:3], v[26:27]
	global_store_dwordx4 v[42:43], v[0:3], off offset:-16
	v_pk_mul_f32 v[26:27], v[60:61], v[32:33] op_sel_hi:[0,1]
	v_pk_mul_f32 v[28:29], v[60:61], v[50:51] op_sel_hi:[0,1]
	v_mov_b64_e32 v[0:1], v[112:113]
	v_mov_b64_e32 v[2:3], v[114:115]
	v_pk_mul_f32 v[0:1], v[0:1], v[28:29]
	v_pk_mul_f32 v[2:3], v[2:3], v[26:27]
	global_store_dwordx4 v[14:15], v[0:3], off offset:-4096
	v_pk_mul_f32 v[26:27], v[60:61], v[52:53] op_sel_hi:[0,1]
	v_pk_mul_f32 v[28:29], v[60:61], v[34:35] op_sel_hi:[0,1]
	v_mov_b64_e32 v[0:1], v[116:117]
	v_mov_b64_e32 v[2:3], v[118:119]
	v_pk_mul_f32 v[0:1], v[0:1], v[26:27]
	v_pk_mul_f32 v[2:3], v[2:3], v[28:29]
	global_store_dwordx4 v[14:15], v[0:3], off offset:-2064
	v_pk_mul_f32 v[26:27], v[60:61], v[54:55] op_sel_hi:[0,1]
	v_pk_mul_f32 v[28:29], v[60:61], v[36:37] op_sel_hi:[0,1]
	v_mov_b64_e32 v[0:1], v[120:121]
	v_mov_b64_e32 v[2:3], v[122:123]
	v_pk_mul_f32 v[0:1], v[0:1], v[26:27]
	v_pk_mul_f32 v[2:3], v[2:3], v[28:29]
	global_store_dwordx4 v[14:15], v[0:3], off offset:-2048
	v_pk_mul_f32 v[26:27], v[60:61], v[56:57] op_sel_hi:[0,1]
	v_pk_mul_f32 v[28:29], v[60:61], v[38:39] op_sel_hi:[0,1]
	v_mov_b64_e32 v[0:1], v[124:125]
	v_mov_b64_e32 v[2:3], v[126:127]
	v_pk_mul_f32 v[0:1], v[0:1], v[26:27]
	v_pk_mul_f32 v[2:3], v[2:3], v[28:29]
	global_store_dwordx4 v[14:15], v[0:3], off offset:-16
	v_pk_mul_f32 v[26:27], v[60:61], v[58:59] op_sel_hi:[0,1]
	v_pk_mul_f32 v[28:29], v[60:61], v[40:41] op_sel_hi:[0,1]
	v_mov_b64_e32 v[0:1], v[128:129]
	v_mov_b64_e32 v[2:3], v[130:131]
	v_pk_mul_f32 v[0:1], v[0:1], v[26:27]
	v_pk_mul_f32 v[2:3], v[2:3], v[28:29]
	global_store_dwordx4 v[14:15], v[0:3], off
	v_lshl_add_u64 v[14:15], v[14:15], 0, s[2:3]
	s_andn2_b64 exec, exec, s[6:7]
	s_cbranch_execnz .LBB0_2010
